# all GEMM K-loops: VALU-free load segments, no s_setprio
# baseline (speedup 1.0000x reference)
; #define PG8_STAGE(bufoff, gbase, voff) do { _Pragma("unroll") for (int _i = 0; _i < 2; ++_i) \
;         __builtin_amdgcn_global_load_lds((const unsigned*)((const char*)(gbase) + (voff)[_i]), (PG8_LAS unsigned*)(lds + (bufoff) + ldsw + _i * 8192), 16, 0, 0); } while (0)
; #define PG8_LDA(dst, b, h) do { _Pragma("unroll") for (int m = 0; m < 4; ++m) _Pragma("unroll") for (int k = 0; k < 2; ++k) dst[m][k] = *(const PG8_LAS bf16x8*)(lds + PG8_SA(b, h) + aoff + m * 2048 + k * 1024); } while (0)
; #define PG8_LDB(dst, b, h) do { _Pragma("unroll") for (int n = 0; n < 2; ++n) _Pragma("unroll") for (int k = 0; k < 2; ++k) dst[n][k] = *(const PG8_LAS bf16x8*)(lds + PG8_SB(b, h) + boff + n * 2048 + k * 1024); } while (0)
; #define PG8_MMA(ai, bj, At, Bt) do { __builtin_amdgcn_s_setprio(1); _Pragma("unroll") for (int m = 0; m < 4; ++m) _Pragma("unroll") for (int n = 0; n < 2; ++n) _Pragma("unroll") for (int k = 0; k < 2; ++k) \
;         acc[ai][bj][m][n] = __builtin_amdgcn_mfma_f32_16x16x32_bf16(Bt[n][k], At[m][k], acc[ai][bj][m][n], 0, 0, 0); __builtin_amdgcn_s_setprio(0); } while (0)
; #define PG8_WAIT_V(n) asm volatile("s_waitcnt vmcnt(" #n ")" ::: "memory")
; #define PG8_WAIT_L(n) asm volatile("s_waitcnt lgkmcnt(" #n ")" ::: "memory")
; #define PG8_BAR __builtin_amdgcn_s_barrier()
; #define PG8_SCHED __builtin_amdgcn_sched_barrier(0)
; template <class Epi, class Sched, bool ALIGN_EPI = false, bool SP2 = false>
; __device__ __forceinline__ void gemm_phase(PG8_LAS unsigned char* lds, const Gemm g, const Sched& S, const Epi& E, const int tid) {
;     ...
;             PG8_LDB(B0, 0, 0); PG8_LDB(B1, 0, 1); PG8_SCHED; PG8_LDA(At, 0, 0); PG8_STAGE(PG8_SA(1, 1), a1 + hstep, voffA);
;             PG8_WAIT_V(8); PG8_WAIT_L(0); PG8_BAR; PG8_MMA(0, 0, At, B0); PG8_MMA(0, 1, At, B1); PG8_BAR; PG8_SCHED;
;     ...
; #pragma unroll
;         for (int a = 0; a < 2; ++a)
; #pragma unroll
;             for (int b = 0; b < 2; ++b)
; #pragma unroll
;                 for (int m = 0; m < 4; ++m)
; #pragma unroll
;                     for (int n = 0; n < 2; ++n) acc[a][b][m][n] = (f32x4){0.f, 0.f, 0.f, 0.f};
;         cur = nxt; cA = nA; cB = nB; ++ui;
.LBB0_617:
	s_add_u32 s68, s68, 0x80
	s_addc_u32 s69, s69, 0
	s_add_u32 s50, s70, 0x100
	v_mov_b32_e32 v2, 0
	s_addc_u32 s51, s71, 0
	s_mov_b32 s70, 0
	v_mov_b32_e32 v3, v2
	v_mov_b32_e32 v4, v2
	v_mov_b32_e32 v5, v2
	v_mov_b32_e32 v6, v2
	v_mov_b32_e32 v7, v2
	v_mov_b32_e32 v8, v2
	v_mov_b32_e32 v9, v2
	v_mov_b32_e32 v18, v2
	v_mov_b32_e32 v19, v2
	v_mov_b32_e32 v20, v2
	v_mov_b32_e32 v21, v2
	v_mov_b32_e32 v22, v2
	v_mov_b32_e32 v23, v2
	v_mov_b32_e32 v24, v2
	v_mov_b32_e32 v25, v2
	v_mov_b32_e32 v34, v2
	v_mov_b32_e32 v35, v2
	v_mov_b32_e32 v36, v2
	v_mov_b32_e32 v37, v2
	v_mov_b32_e32 v38, v2
	v_mov_b32_e32 v39, v2
	v_mov_b32_e32 v40, v2
	v_mov_b32_e32 v41, v2
	v_mov_b32_e32 v50, v2
	v_mov_b32_e32 v51, v2
	v_mov_b32_e32 v52, v2
	v_mov_b32_e32 v53, v2
	v_mov_b32_e32 v54, v2
	v_mov_b32_e32 v55, v2
	v_mov_b32_e32 v56, v2
	v_mov_b32_e32 v57, v2
	v_mov_b32_e32 v10, v2
	v_mov_b32_e32 v11, v2
	v_mov_b32_e32 v12, v2
	v_mov_b32_e32 v13, v2
	v_mov_b32_e32 v14, v2
	v_mov_b32_e32 v15, v2
	v_mov_b32_e32 v16, v2
	v_mov_b32_e32 v17, v2
	v_mov_b32_e32 v26, v2
	v_mov_b32_e32 v27, v2
	v_mov_b32_e32 v28, v2
	v_mov_b32_e32 v29, v2
	v_mov_b32_e32 v30, v2
	v_mov_b32_e32 v31, v2
	v_mov_b32_e32 v32, v2
	v_mov_b32_e32 v33, v2
	v_mov_b32_e32 v42, v2
	v_mov_b32_e32 v43, v2
	v_mov_b32_e32 v44, v2
	v_mov_b32_e32 v45, v2
	v_mov_b32_e32 v46, v2
	v_mov_b32_e32 v47, v2
	v_mov_b32_e32 v48, v2
	v_mov_b32_e32 v49, v2
	v_mov_b32_e32 v58, v2
	v_mov_b32_e32 v59, v2
	v_mov_b32_e32 v60, v2
	v_mov_b32_e32 v61, v2
	v_mov_b32_e32 v62, v2
	v_mov_b32_e32 v63, v2
	v_mov_b32_e32 v64, v2
	v_mov_b32_e32 v65, v2
	v_mov_b32_e32 v66, v2
	v_mov_b32_e32 v67, v2
	v_mov_b32_e32 v68, v2
	v_mov_b32_e32 v69, v2
	v_mov_b32_e32 v70, v2
	v_mov_b32_e32 v71, v2
	v_mov_b32_e32 v72, v2
	v_mov_b32_e32 v73, v2
	s_waitcnt vmcnt(0)
	v_mov_b32_e32 v82, v2
	v_mov_b32_e32 v83, v2
	v_mov_b32_e32 v84, v2
	v_mov_b32_e32 v85, v2
	v_mov_b32_e32 v86, v2
	v_mov_b32_e32 v87, v2
	v_mov_b32_e32 v88, v2
	v_mov_b32_e32 v89, v2
	v_mov_b32_e32 v98, v2
	v_mov_b32_e32 v99, v2
	v_mov_b32_e32 v100, v2
	v_mov_b32_e32 v101, v2
	v_mov_b32_e32 v102, v2
	v_mov_b32_e32 v103, v2
	v_mov_b32_e32 v104, v2
	v_mov_b32_e32 v105, v2
	v_mov_b32_e32 v114, v2
	v_mov_b32_e32 v115, v2
	v_mov_b32_e32 v116, v2
	v_mov_b32_e32 v117, v2
	v_mov_b32_e32 v118, v2
	v_mov_b32_e32 v119, v2
	v_mov_b32_e32 v120, v2
	v_mov_b32_e32 v121, v2
	v_mov_b32_e32 v74, v2
	v_mov_b32_e32 v75, v2
	v_mov_b32_e32 v76, v2
	v_mov_b32_e32 v77, v2
	v_mov_b32_e32 v78, v2
	v_mov_b32_e32 v79, v2
	v_mov_b32_e32 v80, v2
	v_mov_b32_e32 v81, v2
	v_mov_b32_e32 v90, v2
	v_mov_b32_e32 v91, v2
	v_mov_b32_e32 v92, v2
	v_mov_b32_e32 v93, v2
	v_mov_b32_e32 v94, v2
	v_mov_b32_e32 v95, v2
	v_mov_b32_e32 v96, v2
	v_mov_b32_e32 v97, v2
	v_mov_b32_e32 v106, v2
	v_mov_b32_e32 v107, v2
	v_mov_b32_e32 v108, v2
	v_mov_b32_e32 v109, v2
	v_mov_b32_e32 v110, v2
	v_mov_b32_e32 v111, v2
	v_mov_b32_e32 v112, v2
	v_mov_b32_e32 v113, v2
	v_mov_b32_e32 v122, v2
	v_mov_b32_e32 v123, v2
	v_mov_b32_e32 v124, v2
	v_mov_b32_e32 v125, v2
	v_mov_b32_e32 v126, v2
	v_mov_b32_e32 v127, v2
	v_mov_b32_e32 v128, v2
	v_mov_b32_e32 v129, v2
	v_add_u32_e32 v242, 0x10000, v205
.LBB0_618:
	s_add_i32 s85, s70, 2
	s_add_u32 s38, s68, 0x80
	s_addc_u32 s39, s69, 0
	s_add_i32 s59, 0, 0x10000
	s_cmp_eq_u32 s81, s70
	s_cselect_b32 s71, s11, s39
	s_cselect_b32 s70, s10, s38
	s_cselect_b32 s39, s67, s51
	s_cselect_b32 s38, s66, s50
	s_add_i32 s86, 0, 0x14000
	ds_read_b128 v[130:133], v242
	ds_read_b128 v[134:137], v242 offset:1024
	ds_read_b128 v[138:141], v242 offset:2048
	ds_read_b128 v[142:145], v242 offset:3072
	ds_read_b128 v[146:149], v242 offset:16384
	ds_read_b128 v[150:153], v242 offset:17408
	ds_read_b128 v[176:179], v242 offset:18432
	ds_read_b128 v[180:183], v242 offset:19456
	s_add_i32 m0, s73, 0xc000
	ds_read_b128 v[184:187], v207
	ds_read_b128 v[188:191], v207 offset:1024
	ds_read_b128 v[208:211], v207 offset:2048
	ds_read_b128 v[212:215], v207 offset:3072
	ds_read_b128 v[216:219], v207 offset:4096
	ds_read_b128 v[220:223], v207 offset:5120
	ds_read_b128 v[224:227], v207 offset:6144
	ds_read_b128 v[228:231], v207 offset:7168
	global_load_lds_dwordx4 v172, s[68:69]
	s_add_i32 m0, s73, 0xe000
	s_nop 0
	global_load_lds_dwordx4 v174, s[68:69]
	s_waitcnt vmcnt(8)
	s_waitcnt lgkmcnt(0)
	s_barrier
	v_mfma_f32_16x16x32_bf16 v[126:129], v[130:133], v[184:187], v[126:129]
	v_mfma_f32_16x16x32_bf16 v[122:125], v[138:141], v[184:187], v[122:125]
	v_mfma_f32_16x16x32_bf16 v[110:113], v[130:133], v[208:211], v[110:113]
	v_mfma_f32_16x16x32_bf16 v[106:109], v[138:141], v[208:211], v[106:109]
	v_mfma_f32_16x16x32_bf16 v[94:97], v[130:133], v[216:219], v[94:97]
	v_mfma_f32_16x16x32_bf16 v[90:93], v[138:141], v[216:219], v[90:93]
	v_mfma_f32_16x16x32_bf16 v[78:81], v[130:133], v[224:227], v[78:81]
	v_mfma_f32_16x16x32_bf16 v[74:77], v[138:141], v[224:227], v[74:77]
	v_mfma_f32_16x16x32_bf16 v[126:129], v[134:137], v[188:191], v[126:129]
	v_mfma_f32_16x16x32_bf16 v[122:125], v[142:145], v[188:191], v[122:125]
	v_mfma_f32_16x16x32_bf16 v[110:113], v[134:137], v[212:215], v[110:113]
	v_mfma_f32_16x16x32_bf16 v[106:109], v[142:145], v[212:215], v[106:109]
	v_mfma_f32_16x16x32_bf16 v[94:97], v[134:137], v[220:223], v[94:97]
	v_mfma_f32_16x16x32_bf16 v[90:93], v[142:145], v[220:223], v[90:93]
	v_mfma_f32_16x16x32_bf16 v[78:81], v[134:137], v[228:231], v[78:81]
	v_mfma_f32_16x16x32_bf16 v[74:77], v[142:145], v[228:231], v[74:77]
	v_mfma_f32_16x16x32_bf16 v[118:121], v[146:149], v[184:187], v[118:121]
	v_mfma_f32_16x16x32_bf16 v[114:117], v[176:179], v[184:187], v[114:117]
	v_mfma_f32_16x16x32_bf16 v[102:105], v[146:149], v[208:211], v[102:105]
	v_mfma_f32_16x16x32_bf16 v[98:101], v[176:179], v[208:211], v[98:101]
	v_mfma_f32_16x16x32_bf16 v[86:89], v[146:149], v[216:219], v[86:89]
	v_mfma_f32_16x16x32_bf16 v[82:85], v[176:179], v[216:219], v[82:85]
	v_mfma_f32_16x16x32_bf16 v[70:73], v[146:149], v[224:227], v[70:73]
	v_mfma_f32_16x16x32_bf16 v[66:69], v[176:179], v[224:227], v[66:69]
	v_mfma_f32_16x16x32_bf16 v[118:121], v[150:153], v[188:191], v[118:121]
	v_mfma_f32_16x16x32_bf16 v[114:117], v[180:183], v[188:191], v[114:117]
	v_mfma_f32_16x16x32_bf16 v[102:105], v[150:153], v[212:215], v[102:105]
	v_mfma_f32_16x16x32_bf16 v[98:101], v[180:183], v[212:215], v[98:101]
	v_mfma_f32_16x16x32_bf16 v[86:89], v[150:153], v[220:223], v[86:89]
	v_mfma_f32_16x16x32_bf16 v[82:85], v[180:183], v[220:223], v[82:85]
	v_mfma_f32_16x16x32_bf16 v[70:73], v[150:153], v[228:231], v[70:73]
	v_mfma_f32_16x16x32_bf16 v[66:69], v[180:183], v[228:231], v[66:69]
	s_barrier
; #define PG8_STAGE(bufoff, gbase, voff) do { _Pragma("unroll") for (int _i = 0; _i < 2; ++_i) \
;         __builtin_amdgcn_global_load_lds((const unsigned*)((const char*)(gbase) + (voff)[_i]), (PG8_LAS unsigned*)(lds + (bufoff) + ldsw + _i * 8192), 16, 0, 0); } while (0)
; #define PG8_LDA(dst, b, h) do { _Pragma("unroll") for (int m = 0; m < 4; ++m) _Pragma("unroll") for (int k = 0; k < 2; ++k) dst[m][k] = *(const PG8_LAS bf16x8*)(lds + PG8_SA(b, h) + aoff + m * 2048 + k * 1024); } while (0)
; #define PG8_LDB(dst, b, h) do { _Pragma("unroll") for (int n = 0; n < 2; ++n) _Pragma("unroll") for (int k = 0; k < 2; ++k) dst[n][k] = *(const PG8_LAS bf16x8*)(lds + PG8_SB(b, h) + boff + n * 2048 + k * 1024); } while (0)
; #define PG8_MMA(ai, bj, At, Bt) do { __builtin_amdgcn_s_setprio(1); _Pragma("unroll") for (int m = 0; m < 4; ++m) _Pragma("unroll") for (int n = 0; n < 2; ++n) _Pragma("unroll") for (int k = 0; k < 2; ++k) \
;         acc[ai][bj][m][n] = __builtin_amdgcn_mfma_f32_16x16x32_bf16(Bt[n][k], At[m][k], acc[ai][bj][m][n], 0, 0, 0); __builtin_amdgcn_s_setprio(0); } while (0)
; #define PG8_WAIT_V(n) asm volatile("s_waitcnt vmcnt(" #n ")" ::: "memory")
; #define PG8_WAIT_L(n) asm volatile("s_waitcnt lgkmcnt(" #n ")" ::: "memory")
; #define PG8_BAR __builtin_amdgcn_s_barrier()
; #define PG8_SCHED __builtin_amdgcn_sched_barrier(0)
; template <class Epi, class Sched, bool ALIGN_EPI = false, bool SP2 = false>
; __device__ __forceinline__ void gemm_phase(PG8_LAS unsigned char* lds, const Gemm g, const Sched& S, const Epi& E, const int tid) {
;     ...
;             PG8_WAIT_V(8); PG8_WAIT_L(0); PG8_BAR; PG8_MMA(0, 0, At, B0); PG8_MMA(0, 1, At, B1); PG8_BAR; PG8_SCHED;
;             PG8_LDA(At, 0, 1); PG8_STAGE(PG8_SB(0, 0), b2, voffB); PG8_STAGE(PG8_SB(0, 1), b2 + hstep, voffB); PG8_STAGE(PG8_SA(0, 0), a2, voffA);
;             PG8_WAIT_V(8); PG8_WAIT_L(0); PG8_BAR; PG8_MMA(1, 0, At, B0); PG8_MMA(1, 1, At, B1); PG8_BAR; PG8_SCHED;
;             PG8_LDB(B0, 1, 0); PG8_LDB(B1, 1, 1); PG8_SCHED; PG8_LDA(At, 1, 0); PG8_STAGE(PG8_SA(0, 1), a2 + hstep, voffA);
;             PG8_WAIT_V(8); PG8_WAIT_L(0); PG8_BAR; PG8_MMA(0, 0, At, B0); PG8_MMA(0, 1, At, B1); PG8_BAR; PG8_SCHED;
	s_add_i32 s59, s59, s72
	s_mov_b64 s[90:91], s[38:39]
	s_mov_b32 m0, s59
	ds_read_b128 v[184:187], v207 offset:16384
	ds_read_b128 v[188:191], v207 offset:17408
	ds_read_b128 v[208:211], v207 offset:18432
	ds_read_b128 v[212:215], v207 offset:19456
	ds_read_b128 v[216:219], v207 offset:20480
	ds_read_b128 v[220:223], v207 offset:21504
	ds_read_b128 v[224:227], v207 offset:22528
	ds_read_b128 v[228:231], v207 offset:23552
	global_load_lds_dwordx4 v0, s[38:39]
	s_add_i32 m0, s59, 0x2000
	s_add_i32 s59, s86, s72
	global_load_lds_dwordx4 v166, s[38:39]
	s_add_u32 s38, s38, s14
	s_addc_u32 s39, s39, 0
	s_mov_b32 m0, s59
	s_nop 0
	global_load_lds_dwordx4 v0, s[38:39]
	s_add_i32 m0, s59, 0x2000
	s_nop 0
	global_load_lds_dwordx4 v166, s[38:39]
	s_mov_b32 m0, s73
	s_nop 0
	global_load_lds_dwordx4 v170, s[70:71]
	s_mov_b32 m0, s74
	s_nop 0
	global_load_lds_dwordx4 v168, s[70:71]
	s_waitcnt vmcnt(8)
	s_waitcnt lgkmcnt(0)
	s_barrier
	v_mfma_f32_16x16x32_bf16 v[62:65], v[130:133], v[184:187], v[62:65]
	v_mfma_f32_16x16x32_bf16 v[58:61], v[138:141], v[184:187], v[58:61]
	v_mfma_f32_16x16x32_bf16 v[46:49], v[130:133], v[208:211], v[46:49]
	v_mfma_f32_16x16x32_bf16 v[42:45], v[138:141], v[208:211], v[42:45]
	v_mfma_f32_16x16x32_bf16 v[30:33], v[130:133], v[216:219], v[30:33]
	v_mfma_f32_16x16x32_bf16 v[26:29], v[138:141], v[216:219], v[26:29]
	v_mfma_f32_16x16x32_bf16 v[14:17], v[130:133], v[224:227], v[14:17]
	v_mfma_f32_16x16x32_bf16 v[10:13], v[138:141], v[224:227], v[10:13]
	v_mfma_f32_16x16x32_bf16 v[62:65], v[134:137], v[188:191], v[62:65]
	v_mfma_f32_16x16x32_bf16 v[58:61], v[142:145], v[188:191], v[58:61]
	v_mfma_f32_16x16x32_bf16 v[46:49], v[134:137], v[212:215], v[46:49]
	v_mfma_f32_16x16x32_bf16 v[42:45], v[142:145], v[212:215], v[42:45]
	v_mfma_f32_16x16x32_bf16 v[30:33], v[134:137], v[220:223], v[30:33]
	v_mfma_f32_16x16x32_bf16 v[26:29], v[142:145], v[220:223], v[26:29]
	v_mfma_f32_16x16x32_bf16 v[14:17], v[134:137], v[228:231], v[14:17]
	v_mfma_f32_16x16x32_bf16 v[10:13], v[142:145], v[228:231], v[10:13]
	v_mfma_f32_16x16x32_bf16 v[54:57], v[146:149], v[184:187], v[54:57]
	v_mfma_f32_16x16x32_bf16 v[50:53], v[176:179], v[184:187], v[50:53]
	v_mfma_f32_16x16x32_bf16 v[38:41], v[146:149], v[208:211], v[38:41]
	v_mfma_f32_16x16x32_bf16 v[34:37], v[176:179], v[208:211], v[34:37]
	v_mfma_f32_16x16x32_bf16 v[22:25], v[146:149], v[216:219], v[22:25]
	v_mfma_f32_16x16x32_bf16 v[18:21], v[176:179], v[216:219], v[18:21]
	v_mfma_f32_16x16x32_bf16 v[6:9], v[146:149], v[224:227], v[6:9]
	v_mfma_f32_16x16x32_bf16 v[2:5], v[176:179], v[224:227], v[2:5]
	v_mfma_f32_16x16x32_bf16 v[54:57], v[150:153], v[188:191], v[54:57]
	v_mfma_f32_16x16x32_bf16 v[50:53], v[180:183], v[188:191], v[50:53]
	v_mfma_f32_16x16x32_bf16 v[38:41], v[150:153], v[212:215], v[38:41]
	v_mfma_f32_16x16x32_bf16 v[34:37], v[180:183], v[212:215], v[34:37]
	v_mfma_f32_16x16x32_bf16 v[22:25], v[150:153], v[220:223], v[22:25]
	v_mfma_f32_16x16x32_bf16 v[18:21], v[180:183], v[220:223], v[18:21]
	v_mfma_f32_16x16x32_bf16 v[6:9], v[150:153], v[228:231], v[6:9]
	v_mfma_f32_16x16x32_bf16 v[2:5], v[180:183], v[228:231], v[2:5]
	s_barrier
	s_add_i32 s59, 0, 0x18000
	s_add_i32 s86, 0, 0x1c000
	ds_read_b128 v[130:133], v242 offset:32768
	ds_read_b128 v[134:137], v242 offset:33792
	ds_read_b128 v[138:141], v242 offset:34816
	ds_read_b128 v[142:145], v242 offset:35840
	ds_read_b128 v[146:149], v242 offset:49152
	ds_read_b128 v[150:153], v242 offset:50176
	ds_read_b128 v[176:179], v242 offset:51200
	ds_read_b128 v[180:183], v242 offset:52224
	s_add_u32 s38, s70, s14
	s_addc_u32 s39, s71, 0
	s_mov_b32 m0, s75
	ds_read_b128 v[184:187], v207 offset:32768
	ds_read_b128 v[188:191], v207 offset:33792
	ds_read_b128 v[208:211], v207 offset:34816
	ds_read_b128 v[212:215], v207 offset:35840
	ds_read_b128 v[216:219], v207 offset:36864
	ds_read_b128 v[220:223], v207 offset:37888
	ds_read_b128 v[224:227], v207 offset:38912
	ds_read_b128 v[228:231], v207 offset:39936
	global_load_lds_dwordx4 v170, s[38:39]
	s_mov_b32 m0, s76
	s_nop 0
	global_load_lds_dwordx4 v168, s[38:39]
	s_waitcnt vmcnt(8)
	s_waitcnt lgkmcnt(0)
	s_barrier
; #define PG8_STAGE(bufoff, gbase, voff) do { _Pragma("unroll") for (int _i = 0; _i < 2; ++_i) \
;         __builtin_amdgcn_global_load_lds((const unsigned*)((const char*)(gbase) + (voff)[_i]), (PG8_LAS unsigned*)(lds + (bufoff) + ldsw + _i * 8192), 16, 0, 0); } while (0)
; #define PG8_LDA(dst, b, h) do { _Pragma("unroll") for (int m = 0; m < 4; ++m) _Pragma("unroll") for (int k = 0; k < 2; ++k) dst[m][k] = *(const PG8_LAS bf16x8*)(lds + PG8_SA(b, h) + aoff + m * 2048 + k * 1024); } while (0)
; #define PG8_MMA(ai, bj, At, Bt) do { __builtin_amdgcn_s_setprio(1); _Pragma("unroll") for (int m = 0; m < 4; ++m) _Pragma("unroll") for (int n = 0; n < 2; ++n) _Pragma("unroll") for (int k = 0; k < 2; ++k) \
;         acc[ai][bj][m][n] = __builtin_amdgcn_mfma_f32_16x16x32_bf16(Bt[n][k], At[m][k], acc[ai][bj][m][n], 0, 0, 0); __builtin_amdgcn_s_setprio(0); } while (0)
; #define PG8_WAIT_V(n) asm volatile("s_waitcnt vmcnt(" #n ")" ::: "memory")
; #define PG8_WAIT_L(n) asm volatile("s_waitcnt lgkmcnt(" #n ")" ::: "memory")
; #define PG8_BAR __builtin_amdgcn_s_barrier()
; #define PG8_SCHED __builtin_amdgcn_sched_barrier(0)
; template <class Epi, class Sched, bool ALIGN_EPI = false, bool SP2 = false>
; __device__ __forceinline__ void gemm_phase(PG8_LAS unsigned char* lds, const Gemm g, const Sched& S, const Epi& E, const int tid) {
;     ...
;         for (int t = 0; t < nt; t += 2) {
;             const bool last = (t == nt - 2);
;     ...
;             PG8_WAIT_V(8); PG8_WAIT_L(0); PG8_BAR; PG8_MMA(0, 0, At, B0); PG8_MMA(0, 1, At, B1); PG8_BAR; PG8_SCHED;
;             PG8_LDA(At, 1, 1); PG8_STAGE(PG8_SB(1, 0), b3, voffB); PG8_STAGE(PG8_SB(1, 1), b3 + hstep, voffB); PG8_STAGE(PG8_SA(1, 0), a3, voffA);
;             PG8_WAIT_V(8); PG8_WAIT_L(0); PG8_BAR; PG8_MMA(1, 0, At, B0); PG8_MMA(1, 1, At, B1); PG8_BAR; PG8_SCHED;
	v_mfma_f32_16x16x32_bf16 v[126:129], v[130:133], v[184:187], v[126:129]
	v_mfma_f32_16x16x32_bf16 v[122:125], v[138:141], v[184:187], v[122:125]
	v_mfma_f32_16x16x32_bf16 v[110:113], v[130:133], v[208:211], v[110:113]
	v_mfma_f32_16x16x32_bf16 v[106:109], v[138:141], v[208:211], v[106:109]
	v_mfma_f32_16x16x32_bf16 v[94:97], v[130:133], v[216:219], v[94:97]
	v_mfma_f32_16x16x32_bf16 v[90:93], v[138:141], v[216:219], v[90:93]
	v_mfma_f32_16x16x32_bf16 v[78:81], v[130:133], v[224:227], v[78:81]
	v_mfma_f32_16x16x32_bf16 v[74:77], v[138:141], v[224:227], v[74:77]
	v_mfma_f32_16x16x32_bf16 v[126:129], v[134:137], v[188:191], v[126:129]
	v_mfma_f32_16x16x32_bf16 v[122:125], v[142:145], v[188:191], v[122:125]
	v_mfma_f32_16x16x32_bf16 v[110:113], v[134:137], v[212:215], v[110:113]
	v_mfma_f32_16x16x32_bf16 v[106:109], v[142:145], v[212:215], v[106:109]
	v_mfma_f32_16x16x32_bf16 v[94:97], v[134:137], v[220:223], v[94:97]
	v_mfma_f32_16x16x32_bf16 v[90:93], v[142:145], v[220:223], v[90:93]
	v_mfma_f32_16x16x32_bf16 v[78:81], v[134:137], v[228:231], v[78:81]
	v_mfma_f32_16x16x32_bf16 v[74:77], v[142:145], v[228:231], v[74:77]
	v_mfma_f32_16x16x32_bf16 v[118:121], v[146:149], v[184:187], v[118:121]
	v_mfma_f32_16x16x32_bf16 v[114:117], v[176:179], v[184:187], v[114:117]
	v_mfma_f32_16x16x32_bf16 v[102:105], v[146:149], v[208:211], v[102:105]
	v_mfma_f32_16x16x32_bf16 v[98:101], v[176:179], v[208:211], v[98:101]
	v_mfma_f32_16x16x32_bf16 v[86:89], v[146:149], v[216:219], v[86:89]
	v_mfma_f32_16x16x32_bf16 v[82:85], v[176:179], v[216:219], v[82:85]
	v_mfma_f32_16x16x32_bf16 v[70:73], v[146:149], v[224:227], v[70:73]
	v_mfma_f32_16x16x32_bf16 v[66:69], v[176:179], v[224:227], v[66:69]
	v_mfma_f32_16x16x32_bf16 v[118:121], v[150:153], v[188:191], v[118:121]
	v_mfma_f32_16x16x32_bf16 v[114:117], v[180:183], v[188:191], v[114:117]
	v_mfma_f32_16x16x32_bf16 v[102:105], v[150:153], v[212:215], v[102:105]
	v_mfma_f32_16x16x32_bf16 v[98:101], v[180:183], v[212:215], v[98:101]
	v_mfma_f32_16x16x32_bf16 v[86:89], v[150:153], v[220:223], v[86:89]
	v_mfma_f32_16x16x32_bf16 v[82:85], v[180:183], v[220:223], v[82:85]
	v_mfma_f32_16x16x32_bf16 v[70:73], v[150:153], v[228:231], v[70:73]
	v_mfma_f32_16x16x32_bf16 v[66:69], v[180:183], v[228:231], v[66:69]
	s_barrier
	s_add_i32 s38, s59, s72
	s_add_u32 s90, s90, 0x80
	s_addc_u32 s91, s91, 0
	s_mov_b32 m0, s38
	ds_read_b128 v[184:187], v207 offset:49152
	ds_read_b128 v[188:191], v207 offset:50176
	ds_read_b128 v[208:211], v207 offset:51200
	ds_read_b128 v[212:215], v207 offset:52224
	ds_read_b128 v[216:219], v207 offset:53248
	ds_read_b128 v[220:223], v207 offset:54272
	ds_read_b128 v[224:227], v207 offset:55296
	ds_read_b128 v[228:231], v207 offset:56320
	global_load_lds_dwordx4 v0, s[90:91]
	s_add_i32 m0, s38, 0x2000
	s_add_i32 s38, s86, s72
	global_load_lds_dwordx4 v166, s[90:91]
	s_add_u32 s90, s90, s14
	s_addc_u32 s91, s91, 0
	s_mov_b32 m0, s38
	s_nop 0
	global_load_lds_dwordx4 v0, s[90:91]
	s_add_i32 m0, s38, 0x2000
	s_add_u32 s92, s70, 0x80
	s_addc_u32 s93, s71, 0
	global_load_lds_dwordx4 v166, s[90:91]
	s_mov_b32 m0, s79
	s_nop 0
	global_load_lds_dwordx4 v170, s[92:93]
	s_mov_b32 m0, s80
	s_nop 0
	global_load_lds_dwordx4 v168, s[92:93]
	s_waitcnt vmcnt(8)
	s_waitcnt lgkmcnt(0)
	s_barrier
	v_mfma_f32_16x16x32_bf16 v[62:65], v[130:133], v[184:187], v[62:65]
	v_mfma_f32_16x16x32_bf16 v[58:61], v[138:141], v[184:187], v[58:61]
	v_mfma_f32_16x16x32_bf16 v[46:49], v[130:133], v[208:211], v[46:49]
	v_mfma_f32_16x16x32_bf16 v[42:45], v[138:141], v[208:211], v[42:45]
	v_mfma_f32_16x16x32_bf16 v[30:33], v[130:133], v[216:219], v[30:33]
	v_mfma_f32_16x16x32_bf16 v[26:29], v[138:141], v[216:219], v[26:29]
	v_mfma_f32_16x16x32_bf16 v[14:17], v[130:133], v[224:227], v[14:17]
	v_mfma_f32_16x16x32_bf16 v[10:13], v[138:141], v[224:227], v[10:13]
	v_mfma_f32_16x16x32_bf16 v[62:65], v[134:137], v[188:191], v[62:65]
	v_mfma_f32_16x16x32_bf16 v[58:61], v[142:145], v[188:191], v[58:61]
	v_mfma_f32_16x16x32_bf16 v[46:49], v[134:137], v[212:215], v[46:49]
	v_mfma_f32_16x16x32_bf16 v[42:45], v[142:145], v[212:215], v[42:45]
	v_mfma_f32_16x16x32_bf16 v[30:33], v[134:137], v[220:223], v[30:33]
	v_mfma_f32_16x16x32_bf16 v[26:29], v[142:145], v[220:223], v[26:29]
	v_mfma_f32_16x16x32_bf16 v[14:17], v[134:137], v[228:231], v[14:17]
	v_mfma_f32_16x16x32_bf16 v[10:13], v[142:145], v[228:231], v[10:13]
	v_mfma_f32_16x16x32_bf16 v[54:57], v[146:149], v[184:187], v[54:57]
	v_mfma_f32_16x16x32_bf16 v[50:53], v[176:179], v[184:187], v[50:53]
	v_mfma_f32_16x16x32_bf16 v[38:41], v[146:149], v[208:211], v[38:41]
	v_mfma_f32_16x16x32_bf16 v[34:37], v[176:179], v[208:211], v[34:37]
	v_mfma_f32_16x16x32_bf16 v[22:25], v[146:149], v[216:219], v[22:25]
	v_mfma_f32_16x16x32_bf16 v[18:21], v[176:179], v[216:219], v[18:21]
	v_mfma_f32_16x16x32_bf16 v[6:9], v[146:149], v[224:227], v[6:9]
	v_mfma_f32_16x16x32_bf16 v[2:5], v[176:179], v[224:227], v[2:5]
	v_mfma_f32_16x16x32_bf16 v[54:57], v[150:153], v[188:191], v[54:57]
	v_mfma_f32_16x16x32_bf16 v[50:53], v[180:183], v[188:191], v[50:53]
	v_mfma_f32_16x16x32_bf16 v[38:41], v[150:153], v[212:215], v[38:41]
	v_mfma_f32_16x16x32_bf16 v[34:37], v[180:183], v[212:215], v[34:37]
	v_mfma_f32_16x16x32_bf16 v[22:25], v[150:153], v[220:223], v[22:25]
	v_mfma_f32_16x16x32_bf16 v[18:21], v[180:183], v[220:223], v[18:21]
	v_mfma_f32_16x16x32_bf16 v[6:9], v[150:153], v[228:231], v[6:9]
	v_mfma_f32_16x16x32_bf16 v[2:5], v[180:183], v[228:231], v[2:5]
	s_barrier
	s_add_u32 s68, s68, 0x100
	s_addc_u32 s69, s69, 0
	s_add_u32 s50, s50, 0x100
	s_addc_u32 s51, s51, 0
	s_cmp_ge_u32 s85, s78
	s_mov_b32 s70, s85
	s_cbranch_scc0 .LBB0_618
	s_and_b64 vcc, exec, s[22:23]
	s_cbranch_vccz .LBB0_621
	s_barrier
